# v2 + FFN-up tile loads rebalanced 2/4/4/6 + early L1 invalidate in grid barrier
# speedup vs baseline: 1.0236x; 1.0077x over previous
; #define PG8_STAGE(bufoff, gbase, voff) do { _Pragma("unroll") for (int _i = 0; _i < 2; ++_i) \
;         __builtin_amdgcn_global_load_lds((const unsigned*)((const char*)(gbase) + (voff)[_i]), (LAS unsigned*)(lds + (bufoff) + ldsw + _i * 8192), 16, 0, 0); } while (0)
; #define PG8_LDA(dst, b, h) do { _Pragma("unroll") for (int m = 0; m < 4; ++m) _Pragma("unroll") for (int k = 0; k < 2; ++k) dst[m][k] = *(const LAS bf16x8*)(lds + PG8_SA(b, h) + aoff + m * 2048 + k * 1024); } while (0)
; #define PG8_LDB(dst, b, h) do { _Pragma("unroll") for (int n = 0; n < 2; ++n) _Pragma("unroll") for (int k = 0; k < 2; ++k) dst[n][k] = *(const LAS bf16x8*)(lds + PG8_SB(b, h) + boff + n * 2048 + k * 1024); } while (0)
; #define PG8_MMA(ai, bj, At, Bt) do { __builtin_amdgcn_s_setprio(1); _Pragma("unroll") for (int m = 0; m < 4; ++m) _Pragma("unroll") for (int n = 0; n < 2; ++n) _Pragma("unroll") for (int k = 0; k < 2; ++k) \
;         acc[ai][bj][m][n] = __builtin_amdgcn_mfma_f32_16x16x32_bf16(Bt[n][k], At[m][k], acc[ai][bj][m][n], 0, 0, 0); __builtin_amdgcn_s_setprio(0); } while (0)
; #define PG8_BAR __builtin_amdgcn_s_barrier()
; template <class Epi, class Sched>
; __device__ __forceinline__ void gemm_phase(const int tid, LAS unsigned char* lds, const int lda, const int ldb, const int K, const Sched& S, const Epi& E) {
;     ...
;     for (;;) {
;         const bool has_next = S.next(ui + 1, nxt);
;         const char* nA = has_next ? nxt.a : cA; const char* nB = has_next ? nxt.b : cB;
;         for (int t = 0; t < nt; t += 2) {
;             const bool last = (t == nt - 2);
;             const char* a1 = cA + (size_t)(t + 1) * kstep;
;             const char* a2 = last ? nA : cA + (size_t)(t + 2) * kstep; const char* b2 = last ? nB : cB + (size_t)(t + 2) * kstep;
;             const char* a3 = a2 + kstep; const char* b3 = b2 + kstep;
;             PG8_LDB(B0, 0, 0); PG8_LDB(B1, 0, 1); PG8_SCHED; PG8_LDA(At, 0, 0); PG8_STAGE(PG8_SA(1, 1), a1 + hstepA, voffA);
;             PG8_WAIT_V(8); PG8_WAIT_L(0); PG8_BAR; PG8_MMA(0, 0, At, B0); PG8_MMA(0, 1, At, B1); PG8_BAR; PG8_SCHED;
;             PG8_LDA(At, 0, 1); PG8_STAGE(PG8_SB(0, 0), b2, voffB); PG8_STAGE(PG8_SB(0, 1), b2 + hstepB, voffB); PG8_STAGE(PG8_SA(0, 0), a2, voffA);
;             PG8_WAIT_V(8); PG8_WAIT_L(0); PG8_BAR; if (!cur.half) { PG8_MMA(1, 0, At, B0); PG8_MMA(1, 1, At, B1); } PG8_BAR; PG8_SCHED;
.LBB0_896:
	s_add_i32 s65, s52, 2
	s_add_u32 s24, s50, 0xfffc0080
	s_addc_u32 s53, s51, -1
	s_add_i32 s66, 0, 0x10000
	s_cmp_eq_u32 s61, s52
	s_cselect_b32 s55, s3, s53
	s_cselect_b32 s54, s2, s24
	v_add_u32_e32 v166, s66, v146
	s_cselect_b32 s53, s39, s64
	s_cselect_b32 s52, s38, s45
	s_add_i32 s24, 0, 0x14000
	ds_read_b128 v[154:157], v166
	ds_read_b128 v[158:161], v166 offset:1024
	ds_read_b128 v[162:165], v166 offset:2048
	ds_read_b128 v[180:183], v166 offset:3072
	v_add_u32_e32 v166, s24, v146
	ds_read_b128 v[184:187], v166
	ds_read_b128 v[190:193], v166 offset:1024
	ds_read_b128 v[194:197], v166 offset:2048
	ds_read_b128 v[204:207], v166 offset:3072
	v_lshl_add_u64 v[166:167], s[50:51], 0, v[136:137]
	s_add_i32 m0, s29, 0xc000
	ds_read_b128 v[208:211], v153
	ds_read_b128 v[212:215], v153 offset:1024
	ds_read_b128 v[216:219], v153 offset:2048
	ds_read_b128 v[220:223], v153 offset:3072
	ds_read_b128 v[224:227], v153 offset:4096
	ds_read_b128 v[228:231], v153 offset:5120
	ds_read_b128 v[232:235], v153 offset:6144
	ds_read_b128 v[236:239], v153 offset:7168
	global_load_lds_dwordx4 v[166:167], off
	v_lshl_add_u64 v[166:167], s[50:51], 0, v[138:139]
	s_add_i32 m0, s29, 0xe000
	s_nop 0
	global_load_lds_dwordx4 v[166:167], off
	s_waitcnt vmcnt(8)
	s_waitcnt lgkmcnt(0)
	s_barrier
	s_setprio 1
	s_waitcnt lgkmcnt(0)
	v_mfma_f32_16x16x32_bf16 v[124:127], v[154:157], v[208:211], v[124:127]
	v_mfma_f32_16x16x32_bf16 v[116:119], v[162:165], v[208:211], v[116:119]
	v_mfma_f32_16x16x32_bf16 v[108:111], v[154:157], v[216:219], v[108:111]
	v_mfma_f32_16x16x32_bf16 v[100:103], v[162:165], v[216:219], v[100:103]
	v_mfma_f32_16x16x32_bf16 v[92:95], v[154:157], v[224:227], v[92:95]
	v_mfma_f32_16x16x32_bf16 v[84:87], v[162:165], v[224:227], v[84:87]
	v_mfma_f32_16x16x32_bf16 v[76:79], v[154:157], v[232:235], v[76:79]
	v_mfma_f32_16x16x32_bf16 v[68:71], v[162:165], v[232:235], v[68:71]
	v_mfma_f32_16x16x32_bf16 v[124:127], v[158:161], v[212:215], v[124:127]
	v_mfma_f32_16x16x32_bf16 v[116:119], v[180:183], v[212:215], v[116:119]
	v_mfma_f32_16x16x32_bf16 v[108:111], v[158:161], v[220:223], v[108:111]
	v_mfma_f32_16x16x32_bf16 v[100:103], v[180:183], v[220:223], v[100:103]
	v_mfma_f32_16x16x32_bf16 v[92:95], v[158:161], v[228:231], v[92:95]
	v_mfma_f32_16x16x32_bf16 v[84:87], v[180:183], v[228:231], v[84:87]
	v_mfma_f32_16x16x32_bf16 v[76:79], v[158:161], v[236:239], v[76:79]
	v_mfma_f32_16x16x32_bf16 v[68:71], v[180:183], v[236:239], v[68:71]
	s_setprio 0
	s_setprio 1
	v_mfma_f32_16x16x32_bf16 v[120:123], v[184:187], v[208:211], v[120:123]
	v_mfma_f32_16x16x32_bf16 v[112:115], v[194:197], v[208:211], v[112:115]
	v_mfma_f32_16x16x32_bf16 v[104:107], v[184:187], v[216:219], v[104:107]
	v_mfma_f32_16x16x32_bf16 v[96:99], v[194:197], v[216:219], v[96:99]
	v_mfma_f32_16x16x32_bf16 v[88:91], v[184:187], v[224:227], v[88:91]
	v_mfma_f32_16x16x32_bf16 v[80:83], v[194:197], v[224:227], v[80:83]
	v_mfma_f32_16x16x32_bf16 v[72:75], v[184:187], v[232:235], v[72:75]
	v_mfma_f32_16x16x32_bf16 v[64:67], v[194:197], v[232:235], v[64:67]
	v_mfma_f32_16x16x32_bf16 v[120:123], v[190:193], v[212:215], v[120:123]
	v_mfma_f32_16x16x32_bf16 v[112:115], v[204:207], v[212:215], v[112:115]
	v_mfma_f32_16x16x32_bf16 v[104:107], v[190:193], v[220:223], v[104:107]
	v_mfma_f32_16x16x32_bf16 v[96:99], v[204:207], v[220:223], v[96:99]
	v_mfma_f32_16x16x32_bf16 v[88:91], v[190:193], v[228:231], v[88:91]
	v_mfma_f32_16x16x32_bf16 v[80:83], v[204:207], v[228:231], v[80:83]
	v_mfma_f32_16x16x32_bf16 v[72:75], v[190:193], v[236:239], v[72:75]
	v_mfma_f32_16x16x32_bf16 v[64:67], v[204:207], v[236:239], v[64:67]
	s_setprio 0
	s_barrier
	s_add_i32 s66, s66, s20
	v_lshl_add_u64 v[166:167], s[52:53], 0, v[132:133]
	s_mov_b32 m0, s66
	ds_read_b128 v[208:211], v153 offset:16384
	ds_read_b128 v[212:215], v153 offset:17408
	ds_read_b128 v[216:219], v153 offset:18432
	ds_read_b128 v[220:223], v153 offset:19456
	ds_read_b128 v[224:227], v153 offset:20480
	ds_read_b128 v[228:231], v153 offset:21504
	ds_read_b128 v[232:235], v153 offset:22528
	ds_read_b128 v[236:239], v153 offset:23552
	global_load_lds_dwordx4 v[166:167], off
	s_add_i32 m0, s66, 0x2000
	s_add_u32 s66, s52, 0x40000
	v_lshl_add_u64 v[240:241], s[52:53], 0, v[128:129]
	s_addc_u32 s67, s53, 0
	s_add_i32 s24, s24, s20
	global_load_lds_dwordx4 v[240:241], off
	v_lshl_add_u64 v[242:243], s[66:67], 0, v[132:133]
	s_mov_b32 m0, s24
	v_lshl_add_u64 v[244:245], s[54:55], 0, v[130:131]
	global_load_lds_dwordx4 v[242:243], off
	v_lshl_add_u64 v[242:243], s[66:67], 0, v[128:129]
	s_add_i32 m0, s24, 0x2000
	s_nop 0
	global_load_lds_dwordx4 v[242:243], off
	v_lshl_add_u64 v[242:243], s[54:55], 0, v[134:135]
	s_waitcnt vmcnt(6)
	s_waitcnt lgkmcnt(0)
	s_barrier
; #define PG8_STAGE(bufoff, gbase, voff) do { _Pragma("unroll") for (int _i = 0; _i < 2; ++_i) \
;         __builtin_amdgcn_global_load_lds((const unsigned*)((const char*)(gbase) + (voff)[_i]), (LAS unsigned*)(lds + (bufoff) + ldsw + _i * 8192), 16, 0, 0); } while (0)
; #define PG8_LDA(dst, b, h) do { _Pragma("unroll") for (int m = 0; m < 4; ++m) _Pragma("unroll") for (int k = 0; k < 2; ++k) dst[m][k] = *(const LAS bf16x8*)(lds + PG8_SA(b, h) + aoff + m * 2048 + k * 1024); } while (0)
; #define PG8_LDB(dst, b, h) do { _Pragma("unroll") for (int n = 0; n < 2; ++n) _Pragma("unroll") for (int k = 0; k < 2; ++k) dst[n][k] = *(const LAS bf16x8*)(lds + PG8_SB(b, h) + boff + n * 2048 + k * 1024); } while (0)
; #define PG8_MMA(ai, bj, At, Bt) do { __builtin_amdgcn_s_setprio(1); _Pragma("unroll") for (int m = 0; m < 4; ++m) _Pragma("unroll") for (int n = 0; n < 2; ++n) _Pragma("unroll") for (int k = 0; k < 2; ++k) \
;         acc[ai][bj][m][n] = __builtin_amdgcn_mfma_f32_16x16x32_bf16(Bt[n][k], At[m][k], acc[ai][bj][m][n], 0, 0, 0); __builtin_amdgcn_s_setprio(0); } while (0)
; #define PG8_WAIT_V(n) asm volatile("s_waitcnt vmcnt(" #n ")" ::: "memory")
; #define PG8_WAIT_L(n) asm volatile("s_waitcnt lgkmcnt(" #n ")" ::: "memory")
; #define PG8_BAR __builtin_amdgcn_s_barrier()
; #define PG8_SCHED __builtin_amdgcn_sched_barrier(0)
; template <class Epi, class Sched>
; __device__ __forceinline__ void gemm_phase(const int tid, LAS unsigned char* lds, const int lda, const int ldb, const int K, const Sched& S, const Epi& E) {
;     ...
;             PG8_WAIT_V(8); PG8_WAIT_L(0); PG8_BAR; if (!cur.half) { PG8_MMA(1, 0, At, B0); PG8_MMA(1, 1, At, B1); } PG8_BAR; PG8_SCHED;
;             PG8_LDB(B0, 1, 0); PG8_LDB(B1, 1, 1); PG8_SCHED; PG8_LDA(At, 1, 0); PG8_STAGE(PG8_SA(0, 1), a2 + hstepA, voffA);
;             PG8_WAIT_V(8); PG8_WAIT_L(0); PG8_BAR; PG8_MMA(0, 0, At, B0); PG8_MMA(0, 1, At, B1); PG8_BAR; PG8_SCHED;
	s_setprio 1
	s_waitcnt lgkmcnt(0)
	v_mfma_f32_16x16x32_bf16 v[60:63], v[154:157], v[208:211], v[60:63]
	v_mfma_f32_16x16x32_bf16 v[52:55], v[162:165], v[208:211], v[52:55]
	v_mfma_f32_16x16x32_bf16 v[44:47], v[154:157], v[216:219], v[44:47]
	v_mfma_f32_16x16x32_bf16 v[36:39], v[162:165], v[216:219], v[36:39]
	v_mfma_f32_16x16x32_bf16 v[28:31], v[154:157], v[224:227], v[28:31]
	v_mfma_f32_16x16x32_bf16 v[20:23], v[162:165], v[224:227], v[20:23]
	v_mfma_f32_16x16x32_bf16 v[12:15], v[154:157], v[232:235], v[12:15]
	v_mfma_f32_16x16x32_bf16 v[4:7], v[162:165], v[232:235], v[4:7]
	v_mfma_f32_16x16x32_bf16 v[60:63], v[158:161], v[212:215], v[60:63]
	v_mfma_f32_16x16x32_bf16 v[52:55], v[180:183], v[212:215], v[52:55]
	v_mfma_f32_16x16x32_bf16 v[44:47], v[158:161], v[220:223], v[44:47]
	v_mfma_f32_16x16x32_bf16 v[36:39], v[180:183], v[220:223], v[36:39]
	v_mfma_f32_16x16x32_bf16 v[28:31], v[158:161], v[228:231], v[28:31]
	v_mfma_f32_16x16x32_bf16 v[20:23], v[180:183], v[228:231], v[20:23]
	v_mfma_f32_16x16x32_bf16 v[12:15], v[158:161], v[236:239], v[12:15]
	v_mfma_f32_16x16x32_bf16 v[4:7], v[180:183], v[236:239], v[4:7]
	s_setprio 0
	s_setprio 1
	v_mfma_f32_16x16x32_bf16 v[56:59], v[184:187], v[208:211], v[56:59]
	v_mfma_f32_16x16x32_bf16 v[48:51], v[194:197], v[208:211], v[48:51]
	v_mfma_f32_16x16x32_bf16 v[40:43], v[184:187], v[216:219], v[40:43]
	v_mfma_f32_16x16x32_bf16 v[32:35], v[194:197], v[216:219], v[32:35]
	v_mfma_f32_16x16x32_bf16 v[24:27], v[184:187], v[224:227], v[24:27]
	v_mfma_f32_16x16x32_bf16 v[16:19], v[194:197], v[224:227], v[16:19]
	v_mfma_f32_16x16x32_bf16 v[8:11], v[184:187], v[232:235], v[8:11]
	v_mfma_f32_16x16x32_bf16 v[0:3], v[194:197], v[232:235], v[0:3]
	v_mfma_f32_16x16x32_bf16 v[56:59], v[190:193], v[212:215], v[56:59]
	v_mfma_f32_16x16x32_bf16 v[48:51], v[204:207], v[212:215], v[48:51]
	v_mfma_f32_16x16x32_bf16 v[40:43], v[190:193], v[220:223], v[40:43]
	v_mfma_f32_16x16x32_bf16 v[32:35], v[204:207], v[220:223], v[32:35]
	v_mfma_f32_16x16x32_bf16 v[24:27], v[190:193], v[228:231], v[24:27]
	v_mfma_f32_16x16x32_bf16 v[16:19], v[204:207], v[228:231], v[16:19]
	v_mfma_f32_16x16x32_bf16 v[8:11], v[190:193], v[236:239], v[8:11]
	v_mfma_f32_16x16x32_bf16 v[0:3], v[204:207], v[236:239], v[0:3]
	s_setprio 0
	s_barrier
	s_add_i32 s24, 0, 0x18000
	v_add_u32_e32 v176, s24, v146
	s_add_i32 s66, 0, 0x1c000
	ds_read_b128 v[154:157], v176
	ds_read_b128 v[158:161], v176 offset:1024
	ds_read_b128 v[162:165], v176 offset:2048
	ds_read_b128 v[180:183], v176 offset:3072
	v_add_u32_e32 v176, s66, v146
	ds_read_b128 v[184:187], v176
	ds_read_b128 v[190:193], v176 offset:1024
	ds_read_b128 v[194:197], v176 offset:2048
	ds_read_b128 v[204:207], v176 offset:3072
	s_mov_b32 m0, s29
	s_nop 0
	global_load_lds_dwordx4 v[242:243], off
	s_mov_b32 m0, s31
	s_nop 0
	global_load_lds_dwordx4 v[244:245], off
	s_add_u32 s54, s54, 0x40000
	s_addc_u32 s55, s55, 0
	s_mov_b32 m0, s56
	v_lshl_add_u64 v[246:247], s[54:55], 0, v[134:135]
	ds_read_b128 v[208:211], v153 offset:32768
	ds_read_b128 v[212:215], v153 offset:33792
	ds_read_b128 v[216:219], v153 offset:34816
	ds_read_b128 v[220:223], v153 offset:35840
	ds_read_b128 v[224:227], v153 offset:36864
	ds_read_b128 v[228:231], v153 offset:37888
	ds_read_b128 v[232:235], v153 offset:38912
	ds_read_b128 v[236:239], v153 offset:39936
	global_load_lds_dwordx4 v[246:247], off
	v_lshl_add_u64 v[246:247], s[54:55], 0, v[130:131]
	s_mov_b32 m0, s57
	s_nop 0
	global_load_lds_dwordx4 v[246:247], off
	s_waitcnt vmcnt(8)
	s_waitcnt lgkmcnt(0)
	s_barrier
	s_setprio 1
	s_waitcnt lgkmcnt(0)
	v_mfma_f32_16x16x32_bf16 v[124:127], v[154:157], v[208:211], v[124:127]
	v_mfma_f32_16x16x32_bf16 v[116:119], v[162:165], v[208:211], v[116:119]
	v_mfma_f32_16x16x32_bf16 v[108:111], v[154:157], v[216:219], v[108:111]
	v_mfma_f32_16x16x32_bf16 v[100:103], v[162:165], v[216:219], v[100:103]
	v_mfma_f32_16x16x32_bf16 v[92:95], v[154:157], v[224:227], v[92:95]
	v_mfma_f32_16x16x32_bf16 v[84:87], v[162:165], v[224:227], v[84:87]
	v_mfma_f32_16x16x32_bf16 v[76:79], v[154:157], v[232:235], v[76:79]
	v_mfma_f32_16x16x32_bf16 v[68:71], v[162:165], v[232:235], v[68:71]
	v_mfma_f32_16x16x32_bf16 v[124:127], v[158:161], v[212:215], v[124:127]
	v_mfma_f32_16x16x32_bf16 v[116:119], v[180:183], v[212:215], v[116:119]
	v_mfma_f32_16x16x32_bf16 v[108:111], v[158:161], v[220:223], v[108:111]
	v_mfma_f32_16x16x32_bf16 v[100:103], v[180:183], v[220:223], v[100:103]
	v_mfma_f32_16x16x32_bf16 v[92:95], v[158:161], v[228:231], v[92:95]
	v_mfma_f32_16x16x32_bf16 v[84:87], v[180:183], v[228:231], v[84:87]
	v_mfma_f32_16x16x32_bf16 v[76:79], v[158:161], v[236:239], v[76:79]
	v_mfma_f32_16x16x32_bf16 v[68:71], v[180:183], v[236:239], v[68:71]
	s_setprio 0
	s_setprio 1
	v_mfma_f32_16x16x32_bf16 v[120:123], v[184:187], v[208:211], v[120:123]
	v_mfma_f32_16x16x32_bf16 v[112:115], v[194:197], v[208:211], v[112:115]
	v_mfma_f32_16x16x32_bf16 v[104:107], v[184:187], v[216:219], v[104:107]
	v_mfma_f32_16x16x32_bf16 v[96:99], v[194:197], v[216:219], v[96:99]
	v_mfma_f32_16x16x32_bf16 v[88:91], v[184:187], v[224:227], v[88:91]
	v_mfma_f32_16x16x32_bf16 v[80:83], v[194:197], v[224:227], v[80:83]
	v_mfma_f32_16x16x32_bf16 v[72:75], v[184:187], v[232:235], v[72:75]
	v_mfma_f32_16x16x32_bf16 v[64:67], v[194:197], v[232:235], v[64:67]
	v_mfma_f32_16x16x32_bf16 v[120:123], v[190:193], v[212:215], v[120:123]
	v_mfma_f32_16x16x32_bf16 v[112:115], v[204:207], v[212:215], v[112:115]
	v_mfma_f32_16x16x32_bf16 v[104:107], v[190:193], v[220:223], v[104:107]
	v_mfma_f32_16x16x32_bf16 v[96:99], v[204:207], v[220:223], v[96:99]
	v_mfma_f32_16x16x32_bf16 v[88:91], v[190:193], v[228:231], v[88:91]
	v_mfma_f32_16x16x32_bf16 v[80:83], v[204:207], v[228:231], v[80:83]
	v_mfma_f32_16x16x32_bf16 v[72:75], v[190:193], v[236:239], v[72:75]
	v_mfma_f32_16x16x32_bf16 v[64:67], v[204:207], v[236:239], v[64:67]
	s_setprio 0
	s_barrier
; #define PG8_STAGE(bufoff, gbase, voff) do { _Pragma("unroll") for (int _i = 0; _i < 2; ++_i) \
;         __builtin_amdgcn_global_load_lds((const unsigned*)((const char*)(gbase) + (voff)[_i]), (LAS unsigned*)(lds + (bufoff) + ldsw + _i * 8192), 16, 0, 0); } while (0)
; #define PG8_LDA(dst, b, h) do { _Pragma("unroll") for (int m = 0; m < 4; ++m) _Pragma("unroll") for (int k = 0; k < 2; ++k) dst[m][k] = *(const LAS bf16x8*)(lds + PG8_SA(b, h) + aoff + m * 2048 + k * 1024); } while (0)
; #define PG8_MMA(ai, bj, At, Bt) do { __builtin_amdgcn_s_setprio(1); _Pragma("unroll") for (int m = 0; m < 4; ++m) _Pragma("unroll") for (int n = 0; n < 2; ++n) _Pragma("unroll") for (int k = 0; k < 2; ++k) \
;         acc[ai][bj][m][n] = __builtin_amdgcn_mfma_f32_16x16x32_bf16(Bt[n][k], At[m][k], acc[ai][bj][m][n], 0, 0, 0); __builtin_amdgcn_s_setprio(0); } while (0)
; #define PG8_WAIT_V(n) asm volatile("s_waitcnt vmcnt(" #n ")" ::: "memory")
; #define PG8_WAIT_L(n) asm volatile("s_waitcnt lgkmcnt(" #n ")" ::: "memory")
; #define PG8_BAR __builtin_amdgcn_s_barrier()
; #define PG8_SCHED __builtin_amdgcn_sched_barrier(0)
; template <class Epi, class Sched>
; __device__ __forceinline__ void gemm_phase(const int tid, LAS unsigned char* lds, const int lda, const int ldb, const int K, const Sched& S, const Epi& E) {
;     ...
;             PG8_LDA(At, 1, 1); PG8_STAGE(PG8_SB(1, 0), b3, voffB); PG8_STAGE(PG8_SB(1, 1), b3 + hstepB, voffB); PG8_STAGE(PG8_SA(1, 0), a3, voffA);
;             PG8_WAIT_V(8); PG8_WAIT_L(0); PG8_BAR; if (!cur.half) { PG8_MMA(1, 0, At, B0); PG8_MMA(1, 1, At, B1); } PG8_BAR; PG8_SCHED;
;         }
	s_add_i32 s24, s24, s20
	v_lshl_add_u64 v[166:167], v[166:167], 0, s[6:7]
	s_mov_b32 m0, s24
	ds_read_b128 v[208:211], v153 offset:49152
	ds_read_b128 v[212:215], v153 offset:50176
	ds_read_b128 v[216:219], v153 offset:51200
	ds_read_b128 v[220:223], v153 offset:52224
	ds_read_b128 v[224:227], v153 offset:53248
	ds_read_b128 v[228:231], v153 offset:54272
	ds_read_b128 v[232:235], v153 offset:55296
	ds_read_b128 v[236:239], v153 offset:56320
	global_load_lds_dwordx4 v[166:167], off
	s_add_i32 m0, s24, 0x2000
	s_add_u32 s52, s52, 0x40080
	v_lshl_add_u64 v[166:167], v[240:241], 0, s[6:7]
	s_addc_u32 s53, s53, 0
	s_add_i32 s24, s66, s20
	global_load_lds_dwordx4 v[166:167], off
	v_lshl_add_u64 v[166:167], s[52:53], 0, v[132:133]
	s_mov_b32 m0, s24
	s_nop 0
	global_load_lds_dwordx4 v[166:167], off
	v_lshl_add_u64 v[166:167], s[52:53], 0, v[128:129]
	s_add_i32 m0, s24, 0x2000
	s_nop 0
	global_load_lds_dwordx4 v[166:167], off
	v_lshl_add_u64 v[166:167], v[242:243], 0, s[6:7]
	s_mov_b32 m0, s58
	s_nop 0
	global_load_lds_dwordx4 v[166:167], off
	v_lshl_add_u64 v[166:167], v[244:245], 0, s[6:7]
	s_mov_b32 m0, s59
	s_nop 0
	global_load_lds_dwordx4 v[166:167], off
	s_waitcnt vmcnt(8)
	s_waitcnt lgkmcnt(0)
	s_barrier
	s_setprio 1
	s_waitcnt lgkmcnt(0)
	v_mfma_f32_16x16x32_bf16 v[60:63], v[154:157], v[208:211], v[60:63]
	v_mfma_f32_16x16x32_bf16 v[52:55], v[162:165], v[208:211], v[52:55]
	v_mfma_f32_16x16x32_bf16 v[44:47], v[154:157], v[216:219], v[44:47]
	v_mfma_f32_16x16x32_bf16 v[36:39], v[162:165], v[216:219], v[36:39]
	v_mfma_f32_16x16x32_bf16 v[28:31], v[154:157], v[224:227], v[28:31]
	v_mfma_f32_16x16x32_bf16 v[20:23], v[162:165], v[224:227], v[20:23]
	v_mfma_f32_16x16x32_bf16 v[12:15], v[154:157], v[232:235], v[12:15]
	v_mfma_f32_16x16x32_bf16 v[4:7], v[162:165], v[232:235], v[4:7]
	v_mfma_f32_16x16x32_bf16 v[60:63], v[158:161], v[212:215], v[60:63]
	v_mfma_f32_16x16x32_bf16 v[52:55], v[180:183], v[212:215], v[52:55]
	v_mfma_f32_16x16x32_bf16 v[44:47], v[158:161], v[220:223], v[44:47]
	v_mfma_f32_16x16x32_bf16 v[36:39], v[180:183], v[220:223], v[36:39]
	v_mfma_f32_16x16x32_bf16 v[28:31], v[158:161], v[228:231], v[28:31]
	v_mfma_f32_16x16x32_bf16 v[20:23], v[180:183], v[228:231], v[20:23]
	v_mfma_f32_16x16x32_bf16 v[12:15], v[158:161], v[236:239], v[12:15]
	v_mfma_f32_16x16x32_bf16 v[4:7], v[180:183], v[236:239], v[4:7]
	s_setprio 0
	s_setprio 1
	v_mfma_f32_16x16x32_bf16 v[56:59], v[184:187], v[208:211], v[56:59]
	v_mfma_f32_16x16x32_bf16 v[48:51], v[194:197], v[208:211], v[48:51]
	v_mfma_f32_16x16x32_bf16 v[40:43], v[184:187], v[216:219], v[40:43]
	v_mfma_f32_16x16x32_bf16 v[32:35], v[194:197], v[216:219], v[32:35]
	v_mfma_f32_16x16x32_bf16 v[24:27], v[184:187], v[224:227], v[24:27]
	v_mfma_f32_16x16x32_bf16 v[16:19], v[194:197], v[224:227], v[16:19]
	v_mfma_f32_16x16x32_bf16 v[8:11], v[184:187], v[232:235], v[8:11]
	v_mfma_f32_16x16x32_bf16 v[0:3], v[194:197], v[232:235], v[0:3]
	v_mfma_f32_16x16x32_bf16 v[56:59], v[190:193], v[212:215], v[56:59]
	v_mfma_f32_16x16x32_bf16 v[48:51], v[204:207], v[212:215], v[48:51]
	v_mfma_f32_16x16x32_bf16 v[40:43], v[190:193], v[220:223], v[40:43]
	v_mfma_f32_16x16x32_bf16 v[32:35], v[204:207], v[220:223], v[32:35]
	v_mfma_f32_16x16x32_bf16 v[24:27], v[190:193], v[228:231], v[24:27]
	v_mfma_f32_16x16x32_bf16 v[16:19], v[204:207], v[228:231], v[16:19]
	v_mfma_f32_16x16x32_bf16 v[8:11], v[190:193], v[236:239], v[8:11]
	v_mfma_f32_16x16x32_bf16 v[0:3], v[204:207], v[236:239], v[0:3]
	s_setprio 0
	s_barrier
	s_add_u32 s50, s50, 0x100
	s_addc_u32 s51, s51, 0
	s_add_u32 s45, s45, 0x100
	s_addc_u32 s64, s64, 0
	s_cmp_ge_i32 s65, s13
	s_mov_b32 s52, s65
	s_cbranch_scc0 .LBB0_896
	s_mov_b32 s65, 0x12000
	s_mov_b32 s64, 0x14000
	s_mov_b32 s66, 0x16000
	s_mov_b32 s67, 0x18000
	s_and_b64 vcc, exec, s[42:43]
	s_cbranch_vccz .LBB0_899

; __device__ __forceinline__ unsigned xb_ld(unsigned* p)              { return __hip_atomic_load(p, __ATOMIC_RELAXED, __HIP_MEMORY_SCOPE_AGENT); }
; __device__ __forceinline__ unsigned xb_add(unsigned* p, unsigned v) { return __hip_atomic_fetch_add(p, v, __ATOMIC_RELAXED, __HIP_MEMORY_SCOPE_AGENT); }
; #define XB_SPIN(cond, bar) do { unsigned _sp = 0; while (cond) { __builtin_amdgcn_s_sleep(1); \
;     if ((++_sp & 255u) == 0u) { if (xb_ld(&(bar)[XB_TMO])) break; if (_sp > XB_SPIN_CAP) { atomicAdd(&(bar)[XB_TMO], 1u); break; } } } } while (0)
; __device__ __forceinline__ void xcd_barrier(const XcdBarrier& b, int tid) {
;     ...
;         const unsigned old = xb_add(&bar[XB_XSUB(b.x)], 1u);
;         const unsigned gen = old / nloc;
;         if (old + 1u == (gen + 1u) * nloc) {
;             __builtin_amdgcn_fence(__ATOMIC_RELEASE, "agent");
;             asm volatile("s_waitcnt vmcnt(0)" ::: "memory");
;             const unsigned og = xb_add(&bar[XB_TOP], 1u);
;             const unsigned tg = og / nx;
;             if (og + 1u == (tg + 1u) * nx) xb_add(&bar[XB_TOPGEN], 1u);
;             else XB_SPIN(xb_ld(&bar[XB_TOPGEN]) == tg, bar);
;             __builtin_amdgcn_fence(__ATOMIC_ACQUIRE, "agent");
;             xb_add(&bar[XB_XGEN(b.x)], 1u);
;             asm volatile("s_waitcnt vmcnt(0)" ::: "memory");
;         } else {
;             XB_SPIN(xb_ld(&bar[XB_XGEN(b.x)]) == gen, bar);
.LBB0_1023:
	s_or_b64 exec, exec, s[10:11]
	v_cvt_f32_u32_e32 v4, v2
	s_waitcnt vmcnt(0)
	v_readfirstlane_b32 s4, v3
	v_sub_u32_e32 v3, 0, v2
	v_rcp_iflag_f32_e32 v4, v4
	v_add_u32_e32 v5, s4, v1
	v_mul_f32_e32 v4, 0x4f7ffffe, v4
	v_cvt_u32_f32_e32 v4, v4
	v_mul_lo_u32 v1, v3, v4
	v_mul_hi_u32 v1, v4, v1
	v_add_u32_e32 v1, v4, v1
	v_mul_hi_u32 v1, v5, v1
	v_mul_lo_u32 v3, v1, v2
	v_sub_u32_e32 v3, v5, v3
	v_add_u32_e32 v4, 1, v1
	v_cmp_ge_u32_e32 vcc, v3, v2
	s_nop 1
	v_cndmask_b32_e32 v1, v1, v4, vcc
	v_sub_u32_e32 v4, v3, v2
	v_cndmask_b32_e32 v3, v3, v4, vcc
	v_add_u32_e32 v4, 1, v1
	v_cmp_ge_u32_e32 vcc, v3, v2
	v_add_u32_e32 v3, 1, v5
	s_nop 0
	v_cndmask_b32_e32 v1, v1, v4, vcc
	v_mul_lo_u32 v4, v2, v1
	v_add_u32_e32 v2, v4, v2
	v_cmp_ne_u32_e32 vcc, v3, v2
	s_and_saveexec_b64 s[10:11], vcc
	s_xor_b64 s[10:11], exec, s[10:11]
	s_cbranch_execz .LBB0_1037
	buffer_inv sc1
	v_readlane_b32 s12, v254, 40
	v_readlane_b32 s13, v254, 41
	s_waitcnt lgkmcnt(0)
	s_nop 3
	global_load_dword v0, v169, s[12:13] sc1
	s_waitcnt vmcnt(0)
	v_cmp_eq_u32_e32 vcc, v0, v1
	s_and_saveexec_b64 s[12:13], vcc
	s_cbranch_execz .LBB0_1036
	s_mov_b32 s4, 1
	s_mov_b64 s[14:15], 0
	s_branch .LBB0_1027

; __device__ __forceinline__ unsigned xb_ld(unsigned* p)              { return __hip_atomic_load(p, __ATOMIC_RELAXED, __HIP_MEMORY_SCOPE_AGENT); }
; #define XB_SPIN(cond, bar) do { unsigned _sp = 0; while (cond) { __builtin_amdgcn_s_sleep(1); \
;     if ((++_sp & 255u) == 0u) { if (xb_ld(&(bar)[XB_TMO])) break; if (_sp > XB_SPIN_CAP) { atomicAdd(&(bar)[XB_TMO], 1u); break; } } } } while (0)
; __device__ __forceinline__ void xcd_barrier(const XcdBarrier& b, int tid) {
;     ...
;             XB_SPIN(xb_ld(&bar[XB_XGEN(b.x)]) == gen, bar);
;             __builtin_amdgcn_fence(__ATOMIC_ACQUIRE, "agent");
;             asm volatile("s_waitcnt vmcnt(0)" ::: "memory");
.LBB0_1036:
	s_or_b64 exec, exec, s[12:13]
	s_waitcnt vmcnt(0)
	s_nop 0
	s_waitcnt vmcnt(0)
